# attention: persistent -rowmax C-operands and bf16-ones registers, V-fragment LDS addresses folded into ds_read immediates (18 fewer VALU per tile)
# speedup vs baseline: 1.0235x; 1.0046x over previous
; #define AT_DMA(t, buf) do { _Pragma("unroll") for (int j_ = 0; j_ < 7; ++j_) { const int c_ = wid + 8 * j_; if (c_ < 50) { \
;             __builtin_amdgcn_global_load_lds((const unsigned*)dsrc[j_], (LAS unsigned*)(lds + (buf) * AT_BUF + 1024 * c_), 16, 0, 0); dsrc[j_] += dstr[j_]; } } } while (0)
; __device__ __forceinline__ void attn_unit(const Params& P, LAS unsigned char* lds, int bh, int qb) {
;     ...
;     int kxo[4];
; #pragma unroll
;     for (int j = 0; j < 4; ++j) kxo[j] = fr * 512 + (((4 * j + fq) ^ fr) << 4);
;     float mrow[2] = {0.f, 0.f}; f32x4 lacc[2] = {(f32x4){0.f, 0.f, 0.f, 0.f}, (f32x4){0.f, 0.f, 0.f, 0.f}};
;     const bf16x8 ones = {16256, 16256, 16256, 16256, 16256, 16256, 16256, 16256};
;     f32x4 o[8][2];
; #pragma unroll
;     for (int dvb = 0; dvb < 8; ++dvb) { o[dvb][0] = (f32x4){0.f, 0.f, 0.f, 0.f}; o[dvb][1] = (f32x4){0.f, 0.f, 0.f, 0.f}; }
;     AT_DMA(0, 0);
;     asm volatile("s_waitcnt vmcnt(0)" ::: "memory"); __syncthreads();
.LBB0_630:
	v_bfe_u32 v48, v51, 4, 2
	v_xor_b32_e32 v49, v48, v50
	v_lshlrev_b32_e32 v212, 4, v49
	v_bitop3_b32 v49, v48, v50, 4 bitop3:0x36
	v_lshlrev_b32_e32 v213, 4, v49
	v_bitop3_b32 v49, v48, v50, 8 bitop3:0x36
	v_lshlrev_b32_e32 v214, 4, v49
	v_bitop3_b32 v49, v48, v50, 12 bitop3:0x36
	s_waitcnt vmcnt(0)
	v_mov_b32_e32 v76, v173
	v_mov_b32_e32 v77, v173
	v_mov_b32_e32 v78, v173
	v_mov_b32_e32 v79, v173
	v_lshlrev_b32_e32 v210, 3, v48
	v_lshlrev_b32_e32 v211, 9, v50
	v_lshlrev_b32_e32 v216, 4, v49
	s_lshl_b32 s83, s53, 2
	v_lshlrev_b32_e32 v215, 2, v48
	v_or_b32_e32 v217, s81, v50
	v_mul_u32_u24_e32 v218, 0x90, v50
	v_mov_b32_e32 v172, v173
	v_mov_b64_e32 v[114:115], v[78:79]
	v_mov_b64_e32 v[48:49], v[76:77]
	v_mov_b64_e32 v[72:73], v[76:77]
	v_mov_b64_e32 v[52:53], v[76:77]
	v_mov_b64_e32 v[90:91], v[78:79]
	v_mov_b64_e32 v[56:57], v[76:77]
	v_mov_b64_e32 v[94:95], v[78:79]
	v_mov_b64_e32 v[60:61], v[76:77]
	v_mov_b64_e32 v[98:99], v[78:79]
	v_mov_b64_e32 v[64:65], v[76:77]
	v_mov_b64_e32 v[102:103], v[78:79]
	v_mov_b64_e32 v[68:69], v[76:77]
	v_mov_b64_e32 v[106:107], v[78:79]
	v_mov_b64_e32 v[82:83], v[78:79]
	v_mov_b64_e32 v[110:111], v[78:79]
	v_mov_b64_e32 v[86:87], v[78:79]
	v_mov_b64_e32 v[118:119], v[78:79]
	s_xor_b64 s[64:65], s[0:1], -1
	s_add_i32 s83, s83, 4
	v_or_b32_e32 v219, 16, v217
	s_addk_i32 s84, 0x100
	s_mov_b32 s85, 0
	s_mov_b32 s94, 1
	v_mov_b64_e32 v[112:113], v[76:77]
	v_mov_b64_e32 v[50:51], v[78:79]
	v_mov_b64_e32 v[74:75], v[78:79]
	v_mov_b64_e32 v[54:55], v[78:79]
	v_mov_b64_e32 v[88:89], v[76:77]
	v_mov_b64_e32 v[58:59], v[78:79]
	v_mov_b64_e32 v[92:93], v[76:77]
	v_mov_b64_e32 v[62:63], v[78:79]
	v_mov_b64_e32 v[96:97], v[76:77]
	v_mov_b64_e32 v[66:67], v[78:79]
	v_mov_b64_e32 v[100:101], v[76:77]
	v_mov_b64_e32 v[70:71], v[78:79]
	v_mov_b64_e32 v[104:105], v[76:77]
	v_mov_b64_e32 v[80:81], v[76:77]
	v_mov_b64_e32 v[108:109], v[76:77]
	v_mov_b64_e32 v[84:85], v[76:77]
	v_mov_b64_e32 v[116:117], v[76:77]
	v_mov_b64_e32 v[204:205], v[172:173]
	v_mov_b32_e32 v244, 0x80000000
	v_mov_b32_e32 v245, v244
	v_mov_b32_e32 v246, v244
	v_mov_b32_e32 v247, v244
	v_mov_b32_e32 v248, v244
	v_mov_b32_e32 v249, v244
	v_mov_b32_e32 v250, v244
	v_mov_b32_e32 v251, v244
	v_mov_b32_e32 v252, s52
	v_mov_b32_e32 v253, v252
	v_mov_b32_e32 v254, v252
	v_mov_b32_e32 v255, v252
	s_waitcnt vmcnt(0) lgkmcnt(0)
	s_barrier
	s_branch .LBB0_633
; __device__ __forceinline__ unsigned pk2(float lo, float hi) { return pg8::cvtpk(lo, hi); }
; #define MFMA16(a, b, c) __builtin_amdgcn_mfma_f32_16x16x32_bf16((a), (b), (c), 0, 0, 0)
; #define AT_SB __builtin_amdgcn_sched_barrier(0)
; #define AT_VLD(dst, g_) do { _Pragma("unroll") for (int i_ = 0; i_ < 4; ++i_) { const LAS unsigned char* vp = Vl + (16 * (4 * ((g_) & 1) + i_) + fr) * 144 + (32 * ((g_) >> 1) + 4 * fq) * 2; \
;             const u32x2 lo = *(const LAS u32x2*)vp, hi = *(const LAS u32x2*)(vp + 32); u32x4 w; w.x = lo.x; w.y = lo.y; w.z = hi.x; w.w = hi.y; dst[i_] = __builtin_bit_cast(bf16x8, w); } } while (0)
; __device__ __forceinline__ void attn_unit(const Params& P, LAS unsigned char* lds, int bh, int qb) {
;     ...
;             bf16x8 pf[2][2];
; #pragma unroll
;             for (int qk = 0; qk < 2; ++qk) {
; #pragma unroll
;                 for (int kvb = 0; kvb < 4; ++kvb)
; #pragma unroll
;                     for (int e = 0; e < 4; ++e) s[kvb][qk][e] = __builtin_amdgcn_exp2f(s[kvb][qk][e]);
; #pragma unroll
;                 for (int s2 = 0; s2 < 2; ++s2) { u32x4 w; w.x = pk2(s[2 * s2][qk][0], s[2 * s2][qk][1]); w.y = pk2(s[2 * s2][qk][2], s[2 * s2][qk][3]);
;                     w.z = pk2(s[2 * s2 + 1][qk][0], s[2 * s2 + 1][qk][1]); w.w = pk2(s[2 * s2 + 1][qk][2], s[2 * s2 + 1][qk][3]); pf[s2][qk] = __builtin_bit_cast(bf16x8, w); } }
;             AT_SB;
; #pragma unroll
;             for (int g = 0; g < 4; ++g) {
;                 if (g < 3) AT_VLD(vn, g + 1);
;                 AT_SB;
;                 if ((g & 1) == 0) { lacc[0] = MFMA16(ones, pf[g >> 1][0], lacc[0]); lacc[1] = MFMA16(ones, pf[g >> 1][1], lacc[1]); }
; #pragma unroll
;                 for (int i = 0; i < 4; ++i) { const int dvb = 4 * (g & 1) + i; o[dvb][0] = MFMA16(vc[i], pf[g >> 1][0], o[dvb][0]); o[dvb][1] = MFMA16(vc[i], pf[g >> 1][1], o[dvb][1]); }
;                 AT_SB;
;                 if (g < 3) {
; #pragma unroll
;                     for (int i = 0; i < 4; ++i) vc[i] = vn[i]; }
;             }
.LBB0_631:
	v_exp_f32_e32 v160, v160
	v_exp_f32_e32 v161, v161
	v_exp_f32_e32 v162, v162
	v_exp_f32_e32 v163, v163
	v_exp_f32_e32 v164, v164
	v_exp_f32_e32 v165, v165
	v_exp_f32_e32 v166, v166
	v_exp_f32_e32 v167, v167
	v_exp_f32_e32 v156, v156
	v_exp_f32_e32 v157, v157
	v_exp_f32_e32 v158, v158
	v_exp_f32_e32 v159, v159
	v_exp_f32_e32 v206, v152
	v_exp_f32_e32 v207, v153
	v_exp_f32_e32 v224, v154
	v_exp_f32_e32 v225, v155
	v_cvt_pk_bf16_f32 v154, v160, v161
	v_cvt_pk_bf16_f32 v155, v162, v163
	v_exp_f32_e32 v148, v148
	v_exp_f32_e32 v149, v149
	v_exp_f32_e32 v150, v150
	v_exp_f32_e32 v151, v151
	v_exp_f32_e32 v144, v144
	v_exp_f32_e32 v145, v145
	v_exp_f32_e32 v146, v146
	v_exp_f32_e32 v147, v147
	v_exp_f32_e32 v140, v140
	v_exp_f32_e32 v141, v141
	v_exp_f32_e32 v142, v142
	v_exp_f32_e32 v143, v143
	v_exp_f32_e32 v160, v136
	v_exp_f32_e32 v161, v137
	v_exp_f32_e32 v162, v138
	v_exp_f32_e32 v163, v139
	v_cvt_pk_bf16_f32 v152, v164, v165
	v_cvt_pk_bf16_f32 v153, v166, v167
	v_cvt_pk_bf16_f32 v156, v156, v157
	v_cvt_pk_bf16_f32 v157, v158, v159
	v_cvt_pk_bf16_f32 v158, v206, v207
	v_cvt_pk_bf16_f32 v159, v224, v225
	v_cvt_pk_bf16_f32 v136, v148, v149
	v_cvt_pk_bf16_f32 v137, v150, v151
	v_cvt_pk_bf16_f32 v138, v144, v145
	v_cvt_pk_bf16_f32 v139, v146, v147
	v_cvt_pk_bf16_f32 v140, v140, v141
	v_cvt_pk_bf16_f32 v141, v142, v143
	v_cvt_pk_bf16_f32 v142, v160, v161
	v_cvt_pk_bf16_f32 v143, v162, v163
	ds_read_b64 v[144:145], v223 offset:41984
	ds_read_b64 v[146:147], v223 offset:42016
	ds_read_b64 v[148:149], v223 offset:44288
	ds_read_b64 v[150:151], v223 offset:44320
	ds_read_b64 v[160:161], v223 offset:46592
	ds_read_b64 v[162:163], v223 offset:46624
	ds_read_b64 v[164:165], v223 offset:48896
	ds_read_b64 v[166:167], v223 offset:48928
	s_waitcnt lgkmcnt(0)
	v_mfma_f32_16x16x32_bf16 v[116:119], v[120:123], v[152:155], v[116:119]
	v_mfma_f32_16x16x32_bf16 v[112:115], v[252:255], v[152:155], v[112:115]
	v_mfma_f32_16x16x32_bf16 v[76:79], v[252:255], v[136:139], v[76:79]
	v_mfma_f32_16x16x32_bf16 v[84:87], v[120:123], v[136:139], v[84:87]
	v_mfma_f32_16x16x32_bf16 v[108:111], v[124:127], v[152:155], v[108:111]
	v_mfma_f32_16x16x32_bf16 v[80:83], v[124:127], v[136:139], v[80:83]
	v_mfma_f32_16x16x32_bf16 v[104:107], v[128:131], v[152:155], v[104:107]
	v_mfma_f32_16x16x32_bf16 v[68:71], v[128:131], v[136:139], v[68:71]
	v_mfma_f32_16x16x32_bf16 v[100:103], v[132:135], v[152:155], v[100:103]
	v_mfma_f32_16x16x32_bf16 v[64:67], v[132:135], v[136:139], v[64:67]
	ds_read_b64 v[120:121], v223 offset:32832
	ds_read_b64 v[122:123], v223 offset:32864
	ds_read_b64 v[124:125], v223 offset:35136
	ds_read_b64 v[126:127], v223 offset:35168
	ds_read_b64 v[128:129], v223 offset:37440
	ds_read_b64 v[130:131], v223 offset:37472
	ds_read_b64 v[132:133], v223 offset:39744
	ds_read_b64 v[134:135], v223 offset:39776
	v_mfma_f32_16x16x32_bf16 v[96:99], v[144:147], v[152:155], v[96:99]
	v_mfma_f32_16x16x32_bf16 v[60:63], v[144:147], v[136:139], v[60:63]
	v_mfma_f32_16x16x32_bf16 v[92:95], v[148:151], v[152:155], v[92:95]
	v_mfma_f32_16x16x32_bf16 v[56:59], v[148:151], v[136:139], v[56:59]
	v_mfma_f32_16x16x32_bf16 v[88:91], v[160:163], v[152:155], v[88:91]
	v_mfma_f32_16x16x32_bf16 v[52:55], v[160:163], v[136:139], v[52:55]
	v_mfma_f32_16x16x32_bf16 v[72:75], v[164:167], v[152:155], v[72:75]
	v_mfma_f32_16x16x32_bf16 v[48:51], v[164:167], v[136:139], v[48:51]
	ds_read_b64 v[136:137], v223 offset:42048
	ds_read_b64 v[138:139], v223 offset:42080
	ds_read_b64 v[144:145], v223 offset:44352
	ds_read_b64 v[146:147], v223 offset:44384
	ds_read_b64 v[148:149], v223 offset:46656
	ds_read_b64 v[150:151], v223 offset:46688
	ds_read_b64 v[152:153], v223 offset:48960
	ds_read_b64 v[154:155], v223 offset:48992
	v_mfma_f32_16x16x32_bf16 v[112:115], v[252:255], v[156:159], v[112:115]
	v_mfma_f32_16x16x32_bf16 v[76:79], v[252:255], v[140:143], v[76:79]
	s_waitcnt lgkmcnt(0)
	v_mfma_f32_16x16x32_bf16 v[116:119], v[120:123], v[156:159], v[116:119]
	v_mfma_f32_16x16x32_bf16 v[84:87], v[120:123], v[140:143], v[84:87]
	v_mfma_f32_16x16x32_bf16 v[108:111], v[124:127], v[156:159], v[108:111]
	v_mfma_f32_16x16x32_bf16 v[80:83], v[124:127], v[140:143], v[80:83]
	v_mfma_f32_16x16x32_bf16 v[104:107], v[128:131], v[156:159], v[104:107]
	v_mfma_f32_16x16x32_bf16 v[68:71], v[128:131], v[140:143], v[68:71]
	v_mfma_f32_16x16x32_bf16 v[100:103], v[132:135], v[156:159], v[100:103]
	v_mfma_f32_16x16x32_bf16 v[64:67], v[132:135], v[140:143], v[64:67]
	v_mfma_f32_16x16x32_bf16 v[96:99], v[136:139], v[156:159], v[96:99]
	v_mfma_f32_16x16x32_bf16 v[60:63], v[136:139], v[140:143], v[60:63]
	v_mfma_f32_16x16x32_bf16 v[92:95], v[144:147], v[156:159], v[92:95]
	v_mfma_f32_16x16x32_bf16 v[56:59], v[144:147], v[140:143], v[56:59]
	v_mfma_f32_16x16x32_bf16 v[88:91], v[148:151], v[156:159], v[88:91]
	v_mfma_f32_16x16x32_bf16 v[52:55], v[148:151], v[140:143], v[52:55]
	v_mfma_f32_16x16x32_bf16 v[72:75], v[152:155], v[156:159], v[72:75]
	v_mfma_f32_16x16x32_bf16 v[48:51], v[152:155], v[140:143], v[48:51]

; #define MFMA16(a, b, c) __builtin_amdgcn_mfma_f32_16x16x32_bf16((a), (b), (c), 0, 0, 0)
; #define AT_SB __builtin_amdgcn_sched_barrier(0)
; #define AT_KLD(dst, ks_) do { _Pragma("unroll") for (int kvb = 0; kvb < 4; ++kvb) dst[kvb] = *(const LAS bf16x8*)(Kl + kxo[(ks_) & 3] + ((ks_) >> 2) * 256 + kvb * (16 * 512)); } while (0)
; #define AT_VLD(dst, g_) do { _Pragma("unroll") for (int i_ = 0; i_ < 4; ++i_) { const LAS unsigned char* vp = Vl + (16 * (4 * ((g_) & 1) + i_) + fr) * 144 + (32 * ((g_) >> 1) + 4 * fq) * 2; \
;             const u32x2 lo = *(const LAS u32x2*)vp, hi = *(const LAS u32x2*)(vp + 32); u32x4 w; w.x = lo.x; w.y = lo.y; w.z = hi.x; w.w = hi.y; dst[i_] = __builtin_bit_cast(bf16x8, w); } } while (0)
; __device__ __forceinline__ void attn_unit(const Params& P, LAS unsigned char* lds, int bh, int qb) {
;     ...
;         if (k0 <= q0) {
;     ...
;             bf16x8 kc[4], kn[4];
;             AT_KLD(kc, 0);
;             f32x4 s[4][2];
; #pragma unroll
;             for (int kvb = 0; kvb < 4; ++kvb) { s[kvb][0] = (f32x4){-mrow[0], -mrow[0], -mrow[0], -mrow[0]}; s[kvb][1] = (f32x4){-mrow[1], -mrow[1], -mrow[1], -mrow[1]}; }
; #pragma unroll
;             for (int ks = 0; ks < 6; ++ks) {
;                 if (ks < 5) AT_KLD(kn, ks + 1);
;                 AT_SB;
; #pragma unroll
;                 for (int kvb = 0; kvb < 4; ++kvb) { s[kvb][0] = MFMA16(kc[kvb], qf[ks][0], s[kvb][0]); s[kvb][1] = MFMA16(kc[kvb], qf[ks][1], s[kvb][1]); }
;                 AT_SB;
;                 if (ks < 5) {
; #pragma unroll
;                     for (int kvb = 0; kvb < 4; ++kvb) kc[kvb] = kn[kvb]; }
;             }
;             bf16x8 vc[4], vn[4];
;             AT_VLD(vc, 0);
.LBB0_642:
	s_cmp_gt_i32 s85, s81
	s_cbranch_scc1 .LBB0_632
	s_mul_i32 s0, s0, 0xc800
	s_add_i32 s0, s0, 0
	v_add3_u32 v172, s0, v212, v211
	v_add3_u32 v206, s0, v213, v211
	ds_read_b128 v[120:123], v172
	ds_read_b128 v[124:127], v172 offset:8192
	ds_read_b128 v[128:131], v172 offset:16384
	ds_read_b128 v[132:135], v172 offset:24576
	ds_read_b128 v[140:143], v206
	ds_read_b128 v[144:147], v206 offset:8192
	ds_read_b128 v[148:151], v206 offset:16384
	ds_read_b128 v[152:155], v206 offset:24576
	s_waitcnt lgkmcnt(0)
	v_mfma_f32_16x16x32_bf16 v[160:163], v[120:123], v[0:3], v[244:247]
	v_mfma_f32_16x16x32_bf16 v[120:123], v[120:123], v[24:27], v[248:251]
	v_mfma_f32_16x16x32_bf16 v[164:167], v[124:127], v[0:3], v[244:247]
	v_mfma_f32_16x16x32_bf16 v[124:127], v[124:127], v[24:27], v[248:251]
	v_mfma_f32_16x16x32_bf16 v[220:223], v[128:131], v[0:3], v[244:247]
	v_mfma_f32_16x16x32_bf16 v[128:131], v[128:131], v[24:27], v[248:251]
	v_mfma_f32_16x16x32_bf16 v[136:139], v[132:135], v[0:3], v[244:247]
	v_mfma_f32_16x16x32_bf16 v[132:135], v[132:135], v[24:27], v[248:251]
	v_add3_u32 v207, s0, v214, v211
	s_nop 1
	ds_read_b128 v[156:159], v207
	ds_read_b128 v[224:227], v207 offset:8192
	ds_read_b128 v[228:231], v207 offset:16384
	ds_read_b128 v[232:235], v207 offset:24576
	v_mfma_f32_16x16x32_bf16 v[160:163], v[140:143], v[4:7], v[160:163]
	v_mfma_f32_16x16x32_bf16 v[120:123], v[140:143], v[28:31], v[120:123]
	v_mfma_f32_16x16x32_bf16 v[140:143], v[144:147], v[4:7], v[164:167]
	v_mfma_f32_16x16x32_bf16 v[124:127], v[144:147], v[28:31], v[124:127]
	v_mfma_f32_16x16x32_bf16 v[144:147], v[148:151], v[4:7], v[220:223]
	v_mfma_f32_16x16x32_bf16 v[128:131], v[148:151], v[28:31], v[128:131]
	v_mfma_f32_16x16x32_bf16 v[136:139], v[152:155], v[4:7], v[136:139]
	v_mfma_f32_16x16x32_bf16 v[132:135], v[152:155], v[28:31], v[132:135]
	v_add3_u32 v207, s0, v216, v211
	ds_read_b128 v[148:151], v207
	ds_read_b128 v[152:155], v207 offset:8192
	ds_read_b128 v[164:167], v207 offset:16384
	ds_read_b128 v[220:223], v207 offset:24576
	s_waitcnt lgkmcnt(0)
	v_mfma_f32_16x16x32_bf16 v[160:163], v[156:159], v[8:11], v[160:163]
	v_mfma_f32_16x16x32_bf16 v[120:123], v[156:159], v[32:35], v[120:123]
	v_mfma_f32_16x16x32_bf16 v[140:143], v[224:227], v[8:11], v[140:143]
	v_mfma_f32_16x16x32_bf16 v[124:127], v[224:227], v[32:35], v[124:127]
	v_mfma_f32_16x16x32_bf16 v[144:147], v[228:231], v[8:11], v[144:147]
	v_mfma_f32_16x16x32_bf16 v[128:131], v[228:231], v[32:35], v[128:131]
	v_mfma_f32_16x16x32_bf16 v[136:139], v[232:235], v[8:11], v[136:139]
	v_mfma_f32_16x16x32_bf16 v[132:135], v[232:235], v[32:35], v[132:135]
	ds_read_b128 v[156:159], v172 offset:256
	ds_read_b128 v[224:227], v172 offset:8448
	ds_read_b128 v[228:231], v172 offset:16640
	ds_read_b128 v[232:235], v172 offset:24832
	v_mfma_f32_16x16x32_bf16 v[160:163], v[148:151], v[12:15], v[160:163]
	v_mfma_f32_16x16x32_bf16 v[120:123], v[148:151], v[36:39], v[120:123]
	v_mfma_f32_16x16x32_bf16 v[140:143], v[152:155], v[12:15], v[140:143]
	v_mfma_f32_16x16x32_bf16 v[124:127], v[152:155], v[36:39], v[124:127]
	v_mfma_f32_16x16x32_bf16 v[144:147], v[164:167], v[12:15], v[144:147]
	v_mfma_f32_16x16x32_bf16 v[128:131], v[164:167], v[36:39], v[128:131]
	v_mfma_f32_16x16x32_bf16 v[136:139], v[220:223], v[12:15], v[136:139]
	v_mfma_f32_16x16x32_bf16 v[132:135], v[220:223], v[36:39], v[132:135]
	ds_read_b128 v[148:151], v206 offset:256
	ds_read_b128 v[152:155], v206 offset:8448
	ds_read_b128 v[220:223], v206 offset:16640
	ds_read_b128 v[236:239], v206 offset:24832
	s_waitcnt lgkmcnt(0)
	v_mfma_f32_16x16x32_bf16 v[160:163], v[156:159], v[16:19], v[160:163]
	v_mfma_f32_16x16x32_bf16 v[120:123], v[156:159], v[40:43], v[120:123]
	v_mfma_f32_16x16x32_bf16 v[140:143], v[224:227], v[16:19], v[140:143]
	v_mfma_f32_16x16x32_bf16 v[124:127], v[224:227], v[40:43], v[124:127]
	v_mfma_f32_16x16x32_bf16 v[156:159], v[228:231], v[16:19], v[144:147]
	v_mfma_f32_16x16x32_bf16 v[128:131], v[228:231], v[40:43], v[128:131]
	v_mfma_f32_16x16x32_bf16 v[136:139], v[232:235], v[16:19], v[136:139]
	v_mfma_f32_16x16x32_bf16 v[132:135], v[232:235], v[40:43], v[132:135]
	v_mfma_f32_16x16x32_bf16 v[164:167], v[148:151], v[20:23], v[160:163]
	v_mfma_f32_16x16x32_bf16 v[148:151], v[148:151], v[44:47], v[120:123]
	v_mfma_f32_16x16x32_bf16 v[160:163], v[152:155], v[20:23], v[140:143]
	v_mfma_f32_16x16x32_bf16 v[144:147], v[152:155], v[44:47], v[124:127]
	v_mfma_f32_16x16x32_bf16 v[156:159], v[220:223], v[20:23], v[156:159]
	v_mfma_f32_16x16x32_bf16 v[140:143], v[220:223], v[44:47], v[128:131]
	v_mfma_f32_16x16x32_bf16 v[152:155], v[236:239], v[20:23], v[136:139]
	v_mfma_f32_16x16x32_bf16 v[136:139], v[236:239], v[44:47], v[132:135]
	v_add3_u32 v223, s0, v210, v218
	ds_read_b64 v[120:121], v223 offset:32768
	ds_read_b64 v[122:123], v223 offset:32800
	ds_read_b64 v[124:125], v223 offset:35072
	ds_read_b64 v[126:127], v223 offset:35104
	ds_read_b64 v[128:129], v223 offset:37376
	ds_read_b64 v[130:131], v223 offset:37408
	ds_read_b64 v[132:133], v223 offset:39680
	ds_read_b64 v[134:135], v223 offset:39712
	s_add_i32 s0, s85, 63
	s_cmp_le_i32 s0, s81
	s_cbranch_scc1 .LBB0_645
; __device__ __forceinline__ void attn_unit(const Params& P, LAS unsigned char* lds, int bh, int qb) {
;     ...
;             if (k0 + 63 > q0) {
; #pragma unroll
;                 for (int kvb = 0; kvb < 4; ++kvb)
; #pragma unroll
;                     for (int qk = 0; qk < 2; ++qk)
; #pragma unroll
;                         for (int e = 0; e < 4; ++e) { const int kv = k0 + 16 * kvb + 4 * fq + e, q = q0 + 16 * qk + fr; if (kv > q) s[kvb][qk][e] = -INFINITY; }
;             }
	v_add_u32_e32 v207, s85, v215
	v_cmp_gt_i32_e32 vcc, v207, v217
	v_mov_b32_e32 v206, s79
	v_cmp_lt_i32_e64 s[0:1], v207, v217
	v_cndmask_b32_e32 v206, v164, v206, vcc
	v_add_u32_e32 v224, 2, v207
	v_cndmask_b32_e64 v164, v206, v164, s[0:1]
	v_cndmask_b32_e64 v165, v209, v165, s[0:1]
	v_cmp_le_i32_e64 s[0:1], v224, v217
	v_add_u32_e32 v225, 3, v207
	v_mov_b32_e32 v206, s79
	v_cndmask_b32_e64 v166, v209, v166, s[0:1]
	v_cmp_le_i32_e64 s[0:1], v225, v217
	v_add_u32_e32 v226, 19, v207
	v_add_u32_e32 v227, 35, v207
	v_cndmask_b32_e64 v167, v209, v167, s[0:1]
	v_cmp_gt_i32_e64 s[0:1], v207, v219
	s_nop 1
	v_cndmask_b32_e64 v206, v148, v206, s[0:1]
	v_cmp_lt_i32_e64 s[0:1], v207, v219
	s_nop 1
	v_cndmask_b32_e64 v148, v206, v148, s[0:1]
	v_cndmask_b32_e64 v149, v209, v149, s[0:1]
	v_cmp_le_i32_e64 s[0:1], v224, v219
	v_add_u32_e32 v206, 16, v207
	v_add_u32_e32 v224, 17, v207
	v_cndmask_b32_e64 v150, v209, v150, s[0:1]
	v_cmp_le_i32_e64 s[0:1], v225, v219
	v_add_u32_e32 v225, 18, v207
	s_nop 0
	v_cndmask_b32_e64 v151, v209, v151, s[0:1]
	v_cmp_gt_i32_e64 s[0:1], v206, v217
	v_mov_b32_e32 v206, s79
	v_cndmask_b32_e32 v144, v144, v206, vcc
	v_cmp_le_i32_e32 vcc, v224, v219
	v_cndmask_b32_e64 v160, v160, v206, s[0:1]
	v_cmp_le_i32_e64 s[0:1], v224, v217
	v_cndmask_b32_e32 v145, v209, v145, vcc
	v_cmp_le_i32_e32 vcc, v225, v219
	v_add_u32_e32 v224, 32, v207
	v_cndmask_b32_e64 v161, v209, v161, s[0:1]
	v_cndmask_b32_e32 v146, v209, v146, vcc
	v_cmp_le_i32_e32 vcc, v226, v219
	v_cmp_le_i32_e64 s[0:1], v225, v217
	v_add_u32_e32 v225, 33, v207
	v_cndmask_b32_e32 v147, v209, v147, vcc
	v_cmp_gt_i32_e32 vcc, v224, v217
	v_cndmask_b32_e64 v162, v209, v162, s[0:1]
	v_cmp_le_i32_e64 s[0:1], v226, v217
	v_cndmask_b32_e32 v156, v156, v206, vcc
	v_cmp_le_i32_e32 vcc, v225, v217
	v_add_u32_e32 v226, 34, v207
	v_cndmask_b32_e64 v163, v209, v163, s[0:1]
	v_cndmask_b32_e32 v157, v209, v157, vcc
	v_cmp_le_i32_e32 vcc, v226, v217
	s_nop 1
	v_cndmask_b32_e32 v158, v209, v158, vcc
	v_cmp_le_i32_e32 vcc, v227, v217
	s_nop 1
	v_cndmask_b32_e32 v159, v209, v159, vcc
	v_cmp_gt_i32_e32 vcc, v224, v219
	v_add_u32_e32 v224, 48, v207
	s_nop 0
	v_cndmask_b32_e32 v140, v140, v206, vcc
	v_cmp_le_i32_e32 vcc, v225, v219
	v_add_u32_e32 v225, 49, v207
	s_nop 0
	v_cndmask_b32_e32 v141, v209, v141, vcc
	v_cmp_le_i32_e32 vcc, v226, v219
	v_add_u32_e32 v226, 50, v207
	v_add_u32_e32 v207, 51, v207
	v_cndmask_b32_e32 v142, v209, v142, vcc
	v_cmp_le_i32_e32 vcc, v227, v219
	s_nop 1
	v_cndmask_b32_e32 v143, v209, v143, vcc
	v_cmp_gt_i32_e32 vcc, v224, v217
	s_nop 1
	v_cndmask_b32_e32 v152, v152, v206, vcc
	v_cmp_le_i32_e32 vcc, v225, v217
	s_nop 1
	v_cndmask_b32_e32 v153, v209, v153, vcc
	v_cmp_le_i32_e32 vcc, v226, v217
	s_nop 1
	v_cndmask_b32_e32 v154, v209, v154, vcc
	v_cmp_le_i32_e32 vcc, v207, v217
	s_nop 1
	v_cndmask_b32_e32 v155, v209, v155, vcc
	v_cmp_gt_i32_e32 vcc, v224, v219
	s_nop 1
	v_cndmask_b32_e32 v136, v136, v206, vcc
	v_cmp_le_i32_e32 vcc, v225, v219
	s_nop 1
	v_cndmask_b32_e32 v137, v209, v137, vcc
	v_cmp_le_i32_e32 vcc, v226, v219
	s_nop 1
	v_cndmask_b32_e32 v138, v209, v138, vcc
	v_cmp_le_i32_e32 vcc, v207, v219
	s_nop 1
	v_cndmask_b32_e32 v139, v209, v139, vcc

; __device__ __forceinline__ void attn_unit(const Params& P, LAS unsigned char* lds, int bh, int qb) {
;     ...
;             if (t == 0 || __any((mx[0] > AT_THR) || (mx[1] > AT_THR))) {
; #pragma unroll
;                 for (int qk = 0; qk < 2; ++qk) { const float dl = (t == 0) ? mx[qk] : fmaxf(mx[qk], 0.f), alpha = __builtin_amdgcn_exp2f(-dl); mrow[qk] += dl; lacc[qk] *= alpha;
; #pragma unroll
;                     for (int kvb = 0; kvb < 4; ++kvb) s[kvb][qk] -= dl;
; #pragma unroll
;                     for (int dvb = 0; dvb < 8; ++dvb) o[dvb][qk] *= alpha; }
;             }
.LBB0_648:
	s_and_b64 vcc, exec, s[54:55]
	s_cbranch_vccz .LBB0_631
	v_max_f32_e32 v224, 0, v224
	v_cndmask_b32_e64 v206, v224, v206, s[0:1]
	v_exp_f32_e64 v226, -v207
	v_exp_f32_e64 v224, -v206
	v_sub_f32_e32 v164, v164, v207
	v_sub_f32_e32 v165, v165, v207
	v_pk_mul_f32 v[114:115], v[114:115], v[226:227] op_sel_hi:[1,0]
	v_pk_mul_f32 v[112:113], v[112:113], v[226:227] op_sel_hi:[1,0]
	v_sub_f32_e32 v166, v166, v207
	v_sub_f32_e32 v167, v167, v207
	v_sub_f32_e32 v160, v160, v207
	v_sub_f32_e32 v161, v161, v207
	v_sub_f32_e32 v162, v162, v207
	v_sub_f32_e32 v163, v163, v207
	v_sub_f32_e32 v156, v156, v207
	v_sub_f32_e32 v157, v157, v207
	v_sub_f32_e32 v158, v158, v207
	v_sub_f32_e32 v159, v159, v207
	v_sub_f32_e32 v152, v152, v207
	v_sub_f32_e32 v153, v153, v207
	v_sub_f32_e32 v154, v154, v207
	v_sub_f32_e32 v155, v155, v207
	v_pk_mul_f32 v[118:119], v[118:119], v[226:227] op_sel_hi:[1,0]
	v_pk_mul_f32 v[116:117], v[116:117], v[226:227] op_sel_hi:[1,0]
	v_pk_mul_f32 v[110:111], v[110:111], v[226:227] op_sel_hi:[1,0]
	v_pk_mul_f32 v[108:109], v[108:109], v[226:227] op_sel_hi:[1,0]
	v_pk_mul_f32 v[106:107], v[106:107], v[226:227] op_sel_hi:[1,0]
	v_pk_mul_f32 v[104:105], v[104:105], v[226:227] op_sel_hi:[1,0]
	v_pk_mul_f32 v[102:103], v[102:103], v[226:227] op_sel_hi:[1,0]
	v_pk_mul_f32 v[100:101], v[100:101], v[226:227] op_sel_hi:[1,0]
	v_pk_mul_f32 v[98:99], v[98:99], v[226:227] op_sel_hi:[1,0]
	v_pk_mul_f32 v[96:97], v[96:97], v[226:227] op_sel_hi:[1,0]
	v_pk_mul_f32 v[94:95], v[94:95], v[226:227] op_sel_hi:[1,0]
	v_pk_mul_f32 v[92:93], v[92:93], v[226:227] op_sel_hi:[1,0]
	v_pk_mul_f32 v[90:91], v[90:91], v[226:227] op_sel_hi:[1,0]
	v_pk_mul_f32 v[88:89], v[88:89], v[226:227] op_sel_hi:[1,0]
	v_pk_mul_f32 v[74:75], v[74:75], v[226:227] op_sel_hi:[1,0]
	v_pk_mul_f32 v[72:73], v[72:73], v[226:227] op_sel_hi:[1,0]
	v_pk_add_f32 v[204:205], v[204:205], v[206:207]
	v_xor_b32_e32 v244, 0x80000000, v205
	v_xor_b32_e32 v248, 0x80000000, v204
	v_mov_b32_e32 v245, v244
	v_mov_b32_e32 v246, v244
	v_mov_b32_e32 v247, v244
	v_mov_b32_e32 v249, v248
	v_mov_b32_e32 v250, v248
	v_mov_b32_e32 v251, v248
	v_pk_mul_f32 v[78:79], v[78:79], v[224:225] op_sel_hi:[1,0]
	v_pk_mul_f32 v[76:77], v[76:77], v[224:225] op_sel_hi:[1,0]
	v_sub_f32_e32 v148, v148, v206
	v_sub_f32_e32 v149, v149, v206
	v_sub_f32_e32 v150, v150, v206
	v_sub_f32_e32 v151, v151, v206
	v_sub_f32_e32 v144, v144, v206
	v_sub_f32_e32 v145, v145, v206
	v_sub_f32_e32 v146, v146, v206
	v_sub_f32_e32 v147, v147, v206
	v_sub_f32_e32 v140, v140, v206
	v_sub_f32_e32 v141, v141, v206
	v_sub_f32_e32 v142, v142, v206
	v_sub_f32_e32 v143, v143, v206
	v_sub_f32_e32 v136, v136, v206
	v_sub_f32_e32 v137, v137, v206
	v_sub_f32_e32 v138, v138, v206
	v_sub_f32_e32 v139, v139, v206
	v_pk_mul_f32 v[86:87], v[86:87], v[224:225] op_sel_hi:[1,0]
	v_pk_mul_f32 v[84:85], v[84:85], v[224:225] op_sel_hi:[1,0]
	v_pk_mul_f32 v[82:83], v[82:83], v[224:225] op_sel_hi:[1,0]
	v_pk_mul_f32 v[80:81], v[80:81], v[224:225] op_sel_hi:[1,0]
	v_pk_mul_f32 v[70:71], v[70:71], v[224:225] op_sel_hi:[1,0]
	v_pk_mul_f32 v[68:69], v[68:69], v[224:225] op_sel_hi:[1,0]
	v_pk_mul_f32 v[66:67], v[66:67], v[224:225] op_sel_hi:[1,0]
	v_pk_mul_f32 v[64:65], v[64:65], v[224:225] op_sel_hi:[1,0]
	v_pk_mul_f32 v[62:63], v[62:63], v[224:225] op_sel_hi:[1,0]
	v_pk_mul_f32 v[60:61], v[60:61], v[224:225] op_sel_hi:[1,0]
	v_pk_mul_f32 v[58:59], v[58:59], v[224:225] op_sel_hi:[1,0]
	v_pk_mul_f32 v[56:57], v[56:57], v[224:225] op_sel_hi:[1,0]
	v_pk_mul_f32 v[54:55], v[54:55], v[224:225] op_sel_hi:[1,0]
	v_pk_mul_f32 v[52:53], v[52:53], v[224:225] op_sel_hi:[1,0]
	v_pk_mul_f32 v[50:51], v[50:51], v[224:225] op_sel_hi:[1,0]
	v_pk_mul_f32 v[48:49], v[48:49], v[224:225] op_sel_hi:[1,0]
	s_branch .LBB0_631

; __global__ void __launch_bounds__(NTHREADS, 2) hybrid_block_fwd(Params P) {
	.amdhsa_kernel _Z16hybrid_block_fwd6Params
		.amdhsa_group_segment_fixed_size 0
		.amdhsa_private_segment_fixed_size 0
		.amdhsa_kernarg_size 448
		.amdhsa_user_sgpr_count 2
		.amdhsa_user_sgpr_dispatch_ptr 0
		.amdhsa_user_sgpr_queue_ptr 0
		.amdhsa_user_sgpr_kernarg_segment_ptr 1
		.amdhsa_user_sgpr_dispatch_id 0
		.amdhsa_user_sgpr_kernarg_preload_length 0
		.amdhsa_user_sgpr_kernarg_preload_offset 0
		.amdhsa_user_sgpr_private_segment_size 0
		.amdhsa_uses_dynamic_stack 0
		.amdhsa_enable_private_segment 0
		.amdhsa_system_sgpr_workgroup_id_x 1
		.amdhsa_system_sgpr_workgroup_id_y 0
		.amdhsa_system_sgpr_workgroup_id_z 0
		.amdhsa_system_sgpr_workgroup_info 0
		.amdhsa_system_vgpr_workitem_id 2
		.amdhsa_next_free_vgpr 256
		.amdhsa_next_free_sgpr 98
		.amdhsa_accum_offset 256
		.amdhsa_reserve_vcc 1
		.amdhsa_float_round_mode_32 0
		.amdhsa_float_round_mode_16_64 0
		.amdhsa_float_denorm_mode_32 3
		.amdhsa_float_denorm_mode_16_64 3
		.amdhsa_dx10_clamp 1
		.amdhsa_ieee_mode 1
		.amdhsa_fp16_overflow 0
		.amdhsa_tg_split 0
		.amdhsa_exception_fp_ieee_invalid_op 0
		.amdhsa_exception_fp_denorm_src 0
		.amdhsa_exception_fp_ieee_div_zero 0
		.amdhsa_exception_fp_ieee_overflow 0
		.amdhsa_exception_fp_ieee_underflow 0
		.amdhsa_exception_fp_ieee_inexact 0
		.amdhsa_exception_int_div_zero 0
	.end_amdhsa_kernel

; __global__ void __launch_bounds__(NTHREADS, 2) hybrid_block_fwd(Params P) {
.Lfunc_end0:
	.size	_Z16hybrid_block_fwd6Params, .Lfunc_end0-_Z16hybrid_block_fwd6Params
	.set _Z16hybrid_block_fwd6Params.num_vgpr, 256
	.set _Z16hybrid_block_fwd6Params.num_agpr, 0
	.set _Z16hybrid_block_fwd6Params.numbered_sgpr, 98
	.set _Z16hybrid_block_fwd6Params.num_named_barrier, 0
	.set _Z16hybrid_block_fwd6Params.private_seg_size, 0
	.set _Z16hybrid_block_fwd6Params.uses_vcc, 1
	.set _Z16hybrid_block_fwd6Params.uses_flat_scratch, 0
	.set _Z16hybrid_block_fwd6Params.has_dyn_sized_stack, 0
	.set _Z16hybrid_block_fwd6Params.has_recursion, 0
	.set _Z16hybrid_block_fwd6Params.has_indirect_call, 0

; __global__ void __launch_bounds__(NTHREADS, 2) hybrid_block_fwd(Params P) {
amdhsa.kernels:
  - .agpr_count:     0
    .args:
      - .offset:         0
        .size:           192
        .value_kind:     by_value
      - .offset:         192
        .size:           4
        .value_kind:     hidden_block_count_x
      - .offset:         196
        .size:           4
        .value_kind:     hidden_block_count_y
      - .offset:         200
        .size:           4
        .value_kind:     hidden_block_count_z
      - .offset:         204
        .size:           2
        .value_kind:     hidden_group_size_x
      - .offset:         206
        .size:           2
        .value_kind:     hidden_group_size_y
      - .offset:         208
        .size:           2
        .value_kind:     hidden_group_size_z
      - .offset:         210
        .size:           2
        .value_kind:     hidden_remainder_x
      - .offset:         212
        .size:           2
        .value_kind:     hidden_remainder_y
      - .offset:         214
        .size:           2
        .value_kind:     hidden_remainder_z
      - .offset:         232
        .size:           8
        .value_kind:     hidden_global_offset_x
      - .offset:         240
        .size:           8
        .value_kind:     hidden_global_offset_y
      - .offset:         248
        .size:           8
        .value_kind:     hidden_global_offset_z
      - .offset:         256
        .size:           2
        .value_kind:     hidden_grid_dims
      - .offset:         280
        .size:           8
        .value_kind:     hidden_multigrid_sync_arg
      - .offset:         312
        .size:           4
        .value_kind:     hidden_dynamic_lds_size
    .group_segment_fixed_size: 0
    .kernarg_segment_align: 8
    .kernarg_segment_size: 448
    .language:       OpenCL C
    .language_version:
      - 2
      - 0
    .max_flat_workgroup_size: 512
    .name:           _Z16hybrid_block_fwd6Params
    .private_segment_fixed_size: 0
    .sgpr_count:     104
    .sgpr_spill_count: 81
    .symbol:         _Z16hybrid_block_fwd6Params.kd
    .uniform_work_group_size: 1
    .uses_dynamic_stack: false
    .vgpr_count:     256
    .vgpr_spill_count: 0
    .wavefront_size: 64
